# v20 + batched loads in the layer-0 raw-residual ffn_out epilogue
# speedup vs baseline: 1.0113x; 1.0113x over previous
; DEVI void phase_gemm_res(const Params& p, const bf16_t* A, int K, const bf16_t* Bt, const float* xraw, int lnidx, float bscale, bf16_t* smem) {
;     ...
;         if (xraw) {
; #pragma unroll
;             for (int mi = 0; mi < 4; ++mi)
; #pragma unroll
;                 for (int ni = 0; ni < 4; ++ni) {
;                     const size_t idx = (size_t)(tm * 128 + wr * 64 + mi * 16 + l16) * D_ + tn * 128 + wc * 64 + ni * 16 + quad * 4;
;                     const f32x4 rv = *(const f32x4*)(xraw + idx);
;                     *(f32x4*)(hbuf + idx) = rv * ALPHA + acc[mi][ni] * bscale;
;                 }
.LBB0_774:
	s_lshl_b32 s38, s43, 7
	s_ashr_i32 s39, s38, 31
	v_ashrrev_i32_e32 v71, 31, v70
	v_mov_b32_e32 v73, s39
	v_or_b32_e32 v72, s38, v66
	v_lshlrev_b64 v[74:75], 10, v[70:71]
	v_lshl_add_u64 v[74:75], v[74:75], 0, v[72:73]
	v_readlane_b32 s44, v223, 62
	v_lshlrev_b64 v[78:79], 2, v[74:75]
	v_readlane_b32 s45, v223, 63
	s_nop 0
	v_lshl_add_u64 v[128:129], s[10:11], 0, v[78:79]
	v_lshl_add_u64 v[80:81], s[44:45], 0, v[78:79]
	s_mov_b64 s[38:39], 0x10000
	v_lshl_add_u64 v[82:83], v[80:81], 0, s[38:39]
	v_lshl_add_u64 v[130:131], v[128:129], 0, s[38:39]
	v_lshl_add_u64 v[84:85], v[82:83], 0, s[38:39]
	v_lshl_add_u64 v[134:135], v[130:131], 0, s[38:39]
	v_lshl_add_u64 v[86:87], v[84:85], 0, s[38:39]
	v_lshl_add_u64 v[138:139], v[134:135], 0, s[38:39]
	global_load_dwordx4 v[112:115], v[80:81], off
	global_load_dwordx4 v[116:119], v[80:81], off offset:64
	global_load_dwordx4 v[120:123], v[80:81], off offset:128
	global_load_dwordx4 v[124:127], v[80:81], off offset:192
	global_load_dwordx4 v[160:163], v[82:83], off
	global_load_dwordx4 v[164:167], v[82:83], off offset:64
	global_load_dwordx4 v[168:171], v[82:83], off offset:128
	global_load_dwordx4 v[172:175], v[82:83], off offset:192
	global_load_dwordx4 v[176:179], v[84:85], off
	global_load_dwordx4 v[180:183], v[84:85], off offset:64
	global_load_dwordx4 v[184:187], v[84:85], off offset:128
	global_load_dwordx4 v[188:191], v[84:85], off offset:192
	global_load_dwordx4 v[192:195], v[86:87], off
	global_load_dwordx4 v[196:199], v[86:87], off offset:64
	global_load_dwordx4 v[200:203], v[86:87], off offset:128
	global_load_dwordx4 v[216:219], v[86:87], off offset:192
	v_readlane_b32 s46, v222, 0
	v_readlane_b32 s47, v222, 1
	v_readlane_b32 s48, v222, 2
	v_readlane_b32 s49, v222, 3
	v_readlane_b32 s50, v222, 4
	v_readlane_b32 s51, v222, 5
	v_readlane_b32 s52, v222, 6
	v_readlane_b32 s53, v222, 7
	v_readlane_b32 s54, v222, 8
	v_readlane_b32 s55, v222, 9
	v_readlane_b32 s56, v222, 10
	v_readlane_b32 s57, v222, 11
	v_readlane_b32 s58, v222, 12
	v_readlane_b32 s59, v222, 13
	s_waitcnt vmcnt(15)
	v_pk_mul_f32 v[114:115], v[114:115], s[20:21] op_sel_hi:[1,0]
	v_pk_mul_f32 v[112:113], v[112:113], s[20:21] op_sel_hi:[1,0]
	v_pk_fma_f32 v[114:115], v[64:65], 0.5, v[114:115] op_sel_hi:[1,0,1]
	v_pk_fma_f32 v[112:113], v[62:63], 0.5, v[112:113] op_sel_hi:[1,0,1]
	global_store_dwordx4 v[128:129], v[112:115], off
	s_waitcnt vmcnt(15)
	v_pk_mul_f32 v[118:119], v[118:119], s[20:21] op_sel_hi:[1,0]
	v_pk_mul_f32 v[116:117], v[116:117], s[20:21] op_sel_hi:[1,0]
	v_pk_fma_f32 v[118:119], v[60:61], 0.5, v[118:119] op_sel_hi:[1,0,1]
	v_pk_fma_f32 v[116:117], v[58:59], 0.5, v[116:117] op_sel_hi:[1,0,1]
	global_store_dwordx4 v[128:129], v[116:119], off offset:64
	s_waitcnt vmcnt(15)
	v_pk_mul_f32 v[122:123], v[122:123], s[20:21] op_sel_hi:[1,0]
	v_pk_mul_f32 v[120:121], v[120:121], s[20:21] op_sel_hi:[1,0]
	v_pk_fma_f32 v[122:123], v[56:57], 0.5, v[122:123] op_sel_hi:[1,0,1]
	v_pk_fma_f32 v[120:121], v[54:55], 0.5, v[120:121] op_sel_hi:[1,0,1]
	global_store_dwordx4 v[128:129], v[120:123], off offset:128
	s_waitcnt vmcnt(15)
	v_pk_mul_f32 v[126:127], v[126:127], s[20:21] op_sel_hi:[1,0]
	v_pk_mul_f32 v[124:125], v[124:125], s[20:21] op_sel_hi:[1,0]
	v_pk_fma_f32 v[126:127], v[52:53], 0.5, v[126:127] op_sel_hi:[1,0,1]
	v_pk_fma_f32 v[124:125], v[50:51], 0.5, v[124:125] op_sel_hi:[1,0,1]
	global_store_dwordx4 v[128:129], v[124:127], off offset:192
	s_waitcnt vmcnt(15)
	v_pk_mul_f32 v[162:163], v[162:163], s[20:21] op_sel_hi:[1,0]
	v_pk_mul_f32 v[160:161], v[160:161], s[20:21] op_sel_hi:[1,0]
	v_pk_fma_f32 v[162:163], v[48:49], 0.5, v[162:163] op_sel_hi:[1,0,1]
	v_pk_fma_f32 v[160:161], v[46:47], 0.5, v[160:161] op_sel_hi:[1,0,1]
	global_store_dwordx4 v[130:131], v[160:163], off
	s_waitcnt vmcnt(15)
; DEVI void phase_gemm_res(const Params& p, const bf16_t* A, int K, const bf16_t* Bt, const float* xraw, int lnidx, float bscale, bf16_t* smem) {
;     ...
; #pragma unroll
;             for (int mi = 0; mi < 4; ++mi)
; #pragma unroll
;                 for (int ni = 0; ni < 4; ++ni) {
;                     const size_t idx = (size_t)(tm * 128 + wr * 64 + mi * 16 + l16) * D_ + tn * 128 + wc * 64 + ni * 16 + quad * 4;
;                     const f32x4 rv = *(const f32x4*)(xraw + idx);
;                     *(f32x4*)(hbuf + idx) = rv * ALPHA + acc[mi][ni] * bscale;
;                 }
	v_pk_mul_f32 v[166:167], v[166:167], s[20:21] op_sel_hi:[1,0]
	v_pk_mul_f32 v[164:165], v[164:165], s[20:21] op_sel_hi:[1,0]
	v_pk_fma_f32 v[166:167], v[44:45], 0.5, v[166:167] op_sel_hi:[1,0,1]
	v_pk_fma_f32 v[164:165], v[42:43], 0.5, v[164:165] op_sel_hi:[1,0,1]
	global_store_dwordx4 v[130:131], v[164:167], off offset:64
	s_waitcnt vmcnt(15)
	v_pk_mul_f32 v[170:171], v[170:171], s[20:21] op_sel_hi:[1,0]
	v_pk_mul_f32 v[168:169], v[168:169], s[20:21] op_sel_hi:[1,0]
	v_pk_fma_f32 v[170:171], v[40:41], 0.5, v[170:171] op_sel_hi:[1,0,1]
	v_pk_fma_f32 v[168:169], v[38:39], 0.5, v[168:169] op_sel_hi:[1,0,1]
	global_store_dwordx4 v[130:131], v[168:171], off offset:128
	s_waitcnt vmcnt(15)
	v_pk_mul_f32 v[174:175], v[174:175], s[20:21] op_sel_hi:[1,0]
	v_pk_mul_f32 v[172:173], v[172:173], s[20:21] op_sel_hi:[1,0]
	v_pk_fma_f32 v[174:175], v[36:37], 0.5, v[174:175] op_sel_hi:[1,0,1]
	v_pk_fma_f32 v[172:173], v[34:35], 0.5, v[172:173] op_sel_hi:[1,0,1]
	global_store_dwordx4 v[130:131], v[172:175], off offset:192
	s_waitcnt vmcnt(15)
	v_pk_mul_f32 v[178:179], v[178:179], s[20:21] op_sel_hi:[1,0]
	v_pk_mul_f32 v[176:177], v[176:177], s[20:21] op_sel_hi:[1,0]
	v_pk_fma_f32 v[178:179], v[32:33], 0.5, v[178:179] op_sel_hi:[1,0,1]
	v_pk_fma_f32 v[176:177], v[30:31], 0.5, v[176:177] op_sel_hi:[1,0,1]
	global_store_dwordx4 v[134:135], v[176:179], off
	s_waitcnt vmcnt(15)
	v_pk_mul_f32 v[182:183], v[182:183], s[20:21] op_sel_hi:[1,0]
	v_pk_mul_f32 v[180:181], v[180:181], s[20:21] op_sel_hi:[1,0]
	v_pk_fma_f32 v[182:183], v[28:29], 0.5, v[182:183] op_sel_hi:[1,0,1]
	v_pk_fma_f32 v[180:181], v[26:27], 0.5, v[180:181] op_sel_hi:[1,0,1]
	global_store_dwordx4 v[134:135], v[180:183], off offset:64
	s_waitcnt vmcnt(15)
	v_pk_mul_f32 v[186:187], v[186:187], s[20:21] op_sel_hi:[1,0]
	v_pk_mul_f32 v[184:185], v[184:185], s[20:21] op_sel_hi:[1,0]
	v_pk_fma_f32 v[186:187], v[24:25], 0.5, v[186:187] op_sel_hi:[1,0,1]
	v_pk_fma_f32 v[184:185], v[22:23], 0.5, v[184:185] op_sel_hi:[1,0,1]
	global_store_dwordx4 v[134:135], v[184:187], off offset:128
	s_waitcnt vmcnt(15)
	v_pk_mul_f32 v[190:191], v[190:191], s[20:21] op_sel_hi:[1,0]
	v_pk_mul_f32 v[188:189], v[188:189], s[20:21] op_sel_hi:[1,0]
	v_pk_fma_f32 v[190:191], v[20:21], 0.5, v[190:191] op_sel_hi:[1,0,1]
	v_pk_fma_f32 v[188:189], v[18:19], 0.5, v[188:189] op_sel_hi:[1,0,1]
	global_store_dwordx4 v[134:135], v[188:191], off offset:192
	s_waitcnt vmcnt(15)
	v_pk_mul_f32 v[194:195], v[194:195], s[20:21] op_sel_hi:[1,0]
	v_pk_mul_f32 v[192:193], v[192:193], s[20:21] op_sel_hi:[1,0]
	v_pk_fma_f32 v[194:195], v[16:17], 0.5, v[194:195] op_sel_hi:[1,0,1]
	v_pk_fma_f32 v[192:193], v[14:15], 0.5, v[192:193] op_sel_hi:[1,0,1]
	global_store_dwordx4 v[138:139], v[192:195], off
	s_waitcnt vmcnt(15)
	v_pk_mul_f32 v[198:199], v[198:199], s[20:21] op_sel_hi:[1,0]
	v_pk_mul_f32 v[196:197], v[196:197], s[20:21] op_sel_hi:[1,0]
	v_pk_fma_f32 v[198:199], v[8:9], 0.5, v[198:199] op_sel_hi:[1,0,1]
	v_pk_fma_f32 v[196:197], v[6:7], 0.5, v[196:197] op_sel_hi:[1,0,1]
	global_store_dwordx4 v[138:139], v[196:199], off offset:64
	s_waitcnt vmcnt(15)
	v_pk_mul_f32 v[202:203], v[202:203], s[20:21] op_sel_hi:[1,0]
	v_pk_mul_f32 v[200:201], v[200:201], s[20:21] op_sel_hi:[1,0]
	v_pk_fma_f32 v[202:203], v[12:13], 0.5, v[202:203] op_sel_hi:[1,0,1]
	v_pk_fma_f32 v[200:201], v[10:11], 0.5, v[200:201] op_sel_hi:[1,0,1]
	global_store_dwordx4 v[138:139], v[200:203], off offset:128
	s_waitcnt vmcnt(15)
	v_pk_mul_f32 v[218:219], v[218:219], s[20:21] op_sel_hi:[1,0]
	v_pk_mul_f32 v[216:217], v[216:217], s[20:21] op_sel_hi:[1,0]
	v_pk_fma_f32 v[218:219], v[4:5], 0.5, v[218:219] op_sel_hi:[1,0,1]
	v_pk_fma_f32 v[216:217], v[2:3], 0.5, v[216:217] op_sel_hi:[1,0,1]
	global_store_dwordx4 v[138:139], v[216:219], off offset:192
	s_cbranch_execnz .LBB0_755
